# v22 + GEMM K-loop headers aligned to 64 bytes
# baseline (speedup 1.0000x reference)
.LBB0_165:
	s_ashr_i32 s19, s18, 31
	s_lshl_b64 s[20:21], s[18:19], 19
	s_add_u32 s20, s57, s20
	s_addc_u32 s21, s62, s21
	s_and_b64 s[24:25], s[4:5], exec
	s_cselect_b32 s7, s21, s27
	s_cselect_b32 s19, s20, s26
	s_ashr_i32 s17, s16, 31
	s_lshl_b64 s[24:25], s[16:17], 19
	s_add_u32 s24, s3, s24
	s_addc_u32 s25, s22, s25
	s_and_b64 s[30:31], s[4:5], exec
	s_cselect_b32 s17, s25, s29
	s_cselect_b32 s50, s24, s28
	s_add_u32 s26, s26, 0x40080
	s_addc_u32 s27, s27, 0
	s_add_u32 s51, s28, 0x100
	v_mov_b32_e32 v0, 0
	s_addc_u32 s52, s29, 0
	s_mov_b32 s53, -2
	v_mov_b32_e32 v1, v0
	v_mov_b32_e32 v2, v0
	v_mov_b32_e32 v3, v0
	v_mov_b32_e32 v4, v0
	v_mov_b32_e32 v5, v0
	v_mov_b32_e32 v6, v0
	v_mov_b32_e32 v7, v0
	v_mov_b32_e32 v8, v0
	v_mov_b32_e32 v9, v0
	v_mov_b32_e32 v10, v0
	v_mov_b32_e32 v11, v0
	v_mov_b32_e32 v12, v0
	v_mov_b32_e32 v13, v0
	v_mov_b32_e32 v14, v0
	v_mov_b32_e32 v15, v0
	v_mov_b32_e32 v24, v0
	v_mov_b32_e32 v25, v0
	v_mov_b32_e32 v26, v0
	v_mov_b32_e32 v27, v0
	v_mov_b32_e32 v28, v0
	v_mov_b32_e32 v29, v0
	v_mov_b32_e32 v30, v0
	v_mov_b32_e32 v31, v0
	v_mov_b32_e32 v40, v0
	v_mov_b32_e32 v41, v0
	v_mov_b32_e32 v42, v0
	v_mov_b32_e32 v43, v0
	v_mov_b32_e32 v44, v0
	v_mov_b32_e32 v45, v0
	v_mov_b32_e32 v46, v0
	v_mov_b32_e32 v47, v0
	v_mov_b32_e32 v16, v0
	v_mov_b32_e32 v17, v0
	v_mov_b32_e32 v18, v0
	v_mov_b32_e32 v19, v0
	v_mov_b32_e32 v20, v0
	v_mov_b32_e32 v21, v0
	v_mov_b32_e32 v22, v0
	v_mov_b32_e32 v23, v0
	v_mov_b32_e32 v32, v0
	v_mov_b32_e32 v33, v0
	v_mov_b32_e32 v34, v0
	v_mov_b32_e32 v35, v0
	v_mov_b32_e32 v36, v0
	v_mov_b32_e32 v37, v0
	v_mov_b32_e32 v38, v0
	v_mov_b32_e32 v39, v0
	v_mov_b32_e32 v48, v0
	v_mov_b32_e32 v49, v0
	v_mov_b32_e32 v50, v0
	v_mov_b32_e32 v51, v0
	v_mov_b32_e32 v52, v0
	v_mov_b32_e32 v53, v0
	v_mov_b32_e32 v54, v0
	v_mov_b32_e32 v55, v0
	v_mov_b32_e32 v56, v0
	v_mov_b32_e32 v57, v0
	v_mov_b32_e32 v58, v0
	v_mov_b32_e32 v59, v0
	v_mov_b32_e32 v60, v0
	v_mov_b32_e32 v61, v0
	v_mov_b32_e32 v62, v0
	v_mov_b32_e32 v63, v0
	v_mov_b32_e32 v64, v0
	v_mov_b32_e32 v65, v0
	v_mov_b32_e32 v66, v0
	v_mov_b32_e32 v67, v0
	v_mov_b32_e32 v68, v0
	v_mov_b32_e32 v69, v0
	v_mov_b32_e32 v70, v0
	v_mov_b32_e32 v71, v0
	v_mov_b32_e32 v72, v0
	v_mov_b32_e32 v73, v0
	v_mov_b32_e32 v74, v0
	v_mov_b32_e32 v75, v0
	v_mov_b32_e32 v76, v0
	v_mov_b32_e32 v77, v0
	v_mov_b32_e32 v78, v0
	v_mov_b32_e32 v79, v0
	v_mov_b32_e32 v88, v0
	v_mov_b32_e32 v89, v0
	v_mov_b32_e32 v90, v0
	v_mov_b32_e32 v91, v0
	v_mov_b32_e32 v92, v0
	v_mov_b32_e32 v93, v0
	v_mov_b32_e32 v94, v0
	v_mov_b32_e32 v95, v0
	v_mov_b32_e32 v104, v0
	v_mov_b32_e32 v105, v0
	v_mov_b32_e32 v106, v0
	v_mov_b32_e32 v107, v0
	v_mov_b32_e32 v108, v0
	v_mov_b32_e32 v109, v0
	v_mov_b32_e32 v110, v0
	v_mov_b32_e32 v111, v0
	v_mov_b32_e32 v80, v0
	v_mov_b32_e32 v81, v0
	v_mov_b32_e32 v82, v0
	v_mov_b32_e32 v83, v0
	v_mov_b32_e32 v84, v0
	v_mov_b32_e32 v85, v0
	v_mov_b32_e32 v86, v0
	v_mov_b32_e32 v87, v0
	v_mov_b32_e32 v96, v0
	v_mov_b32_e32 v97, v0
	v_mov_b32_e32 v98, v0
	v_mov_b32_e32 v99, v0
	v_mov_b32_e32 v100, v0
	v_mov_b32_e32 v101, v0
	v_mov_b32_e32 v102, v0
	v_mov_b32_e32 v103, v0
	v_mov_b32_e32 v112, v0
	v_mov_b32_e32 v113, v0
	v_mov_b32_e32 v114, v0
	v_mov_b32_e32 v115, v0
	v_mov_b32_e32 v116, v0
	v_mov_b32_e32 v117, v0
	v_mov_b32_e32 v118, v0
	v_mov_b32_e32 v119, v0
	v_mov_b32_e32 v120, v0
	v_mov_b32_e32 v121, v0
	v_mov_b32_e32 v122, v0
	v_mov_b32_e32 v123, v0
	v_mov_b32_e32 v124, v0
	v_mov_b32_e32 v125, v0
	v_mov_b32_e32 v126, v0
	v_mov_b32_e32 v127, v0
	.p2align	6

.LBB0_205:
	s_ashr_i32 s15, s14, 31
	s_lshl_b64 s[20:21], s[14:15], 19
	s_add_u32 s20, s81, s20
	s_addc_u32 s21, s47, s21
	s_and_b64 s[24:25], s[4:5], exec
	s_cselect_b32 s15, s21, s27
	s_cselect_b32 s49, s20, s26
	s_ashr_i32 s13, s12, 31
	s_lshl_b64 s[24:25], s[12:13], 19
	s_add_u32 s24, s57, s24
	s_addc_u32 s25, s62, s25
	s_and_b64 s[30:31], s[4:5], exec
	s_cselect_b32 s13, s25, s29
	s_cselect_b32 s50, s24, s28
	s_add_u32 s26, s26, 0x40080
	s_addc_u32 s27, s27, 0
	s_add_u32 s51, s28, 0x100
	v_mov_b32_e32 v0, 0
	s_addc_u32 s52, s29, 0
	s_mov_b32 s53, -2
	v_mov_b32_e32 v1, v0
	v_mov_b32_e32 v2, v0
	v_mov_b32_e32 v3, v0
	v_mov_b32_e32 v4, v0
	v_mov_b32_e32 v5, v0
	v_mov_b32_e32 v6, v0
	v_mov_b32_e32 v7, v0
	v_mov_b32_e32 v8, v0
	v_mov_b32_e32 v9, v0
	v_mov_b32_e32 v10, v0
	v_mov_b32_e32 v11, v0
	v_mov_b32_e32 v12, v0
	v_mov_b32_e32 v13, v0
	v_mov_b32_e32 v14, v0
	v_mov_b32_e32 v15, v0
	v_mov_b32_e32 v24, v0
	v_mov_b32_e32 v25, v0
	v_mov_b32_e32 v26, v0
	v_mov_b32_e32 v27, v0
	v_mov_b32_e32 v28, v0
	v_mov_b32_e32 v29, v0
	v_mov_b32_e32 v30, v0
	v_mov_b32_e32 v31, v0
	v_mov_b32_e32 v40, v0
	v_mov_b32_e32 v41, v0
	v_mov_b32_e32 v42, v0
	v_mov_b32_e32 v43, v0
	v_mov_b32_e32 v44, v0
	v_mov_b32_e32 v45, v0
	v_mov_b32_e32 v46, v0
	v_mov_b32_e32 v47, v0
	v_mov_b32_e32 v16, v0
	v_mov_b32_e32 v17, v0
	v_mov_b32_e32 v18, v0
	v_mov_b32_e32 v19, v0
	v_mov_b32_e32 v20, v0
	v_mov_b32_e32 v21, v0
	v_mov_b32_e32 v22, v0
	v_mov_b32_e32 v23, v0
	v_mov_b32_e32 v32, v0
	v_mov_b32_e32 v33, v0
	v_mov_b32_e32 v34, v0
	v_mov_b32_e32 v35, v0
	v_mov_b32_e32 v36, v0
	v_mov_b32_e32 v37, v0
	v_mov_b32_e32 v38, v0
	v_mov_b32_e32 v39, v0
	v_mov_b32_e32 v48, v0
	v_mov_b32_e32 v49, v0
	v_mov_b32_e32 v50, v0
	v_mov_b32_e32 v51, v0
	v_mov_b32_e32 v52, v0
	v_mov_b32_e32 v53, v0
	v_mov_b32_e32 v54, v0
	v_mov_b32_e32 v55, v0
	v_mov_b32_e32 v56, v0
	v_mov_b32_e32 v57, v0
	v_mov_b32_e32 v58, v0
	v_mov_b32_e32 v59, v0
	v_mov_b32_e32 v60, v0
	v_mov_b32_e32 v61, v0
	v_mov_b32_e32 v62, v0
	v_mov_b32_e32 v63, v0
	v_mov_b32_e32 v64, v0
	v_mov_b32_e32 v65, v0
	v_mov_b32_e32 v66, v0
	v_mov_b32_e32 v67, v0
	v_mov_b32_e32 v68, v0
	v_mov_b32_e32 v69, v0
	v_mov_b32_e32 v70, v0
	v_mov_b32_e32 v71, v0
	v_mov_b32_e32 v72, v0
	v_mov_b32_e32 v73, v0
	v_mov_b32_e32 v74, v0
	v_mov_b32_e32 v75, v0
	v_mov_b32_e32 v76, v0
	v_mov_b32_e32 v77, v0
	v_mov_b32_e32 v78, v0
	v_mov_b32_e32 v79, v0
	v_mov_b32_e32 v88, v0
	v_mov_b32_e32 v89, v0
	v_mov_b32_e32 v90, v0
	v_mov_b32_e32 v91, v0
	v_mov_b32_e32 v92, v0
	v_mov_b32_e32 v93, v0
	v_mov_b32_e32 v94, v0
	v_mov_b32_e32 v95, v0
	v_mov_b32_e32 v104, v0
	v_mov_b32_e32 v105, v0
	v_mov_b32_e32 v106, v0
	v_mov_b32_e32 v107, v0
	v_mov_b32_e32 v108, v0
	v_mov_b32_e32 v109, v0
	v_mov_b32_e32 v110, v0
	v_mov_b32_e32 v111, v0
	v_mov_b32_e32 v80, v0
	v_mov_b32_e32 v81, v0
	v_mov_b32_e32 v82, v0
	v_mov_b32_e32 v83, v0
	v_mov_b32_e32 v84, v0
	v_mov_b32_e32 v85, v0
	v_mov_b32_e32 v86, v0
	v_mov_b32_e32 v87, v0
	v_mov_b32_e32 v96, v0
	v_mov_b32_e32 v97, v0
	v_mov_b32_e32 v98, v0
	v_mov_b32_e32 v99, v0
	v_mov_b32_e32 v100, v0
	v_mov_b32_e32 v101, v0
	v_mov_b32_e32 v102, v0
	v_mov_b32_e32 v103, v0
	v_mov_b32_e32 v112, v0
	v_mov_b32_e32 v113, v0
	v_mov_b32_e32 v114, v0
	v_mov_b32_e32 v115, v0
	v_mov_b32_e32 v116, v0
	v_mov_b32_e32 v117, v0
	v_mov_b32_e32 v118, v0
	v_mov_b32_e32 v119, v0
	v_mov_b32_e32 v120, v0
	v_mov_b32_e32 v121, v0
	v_mov_b32_e32 v122, v0
	v_mov_b32_e32 v123, v0
	v_mov_b32_e32 v124, v0
	v_mov_b32_e32 v125, v0
	v_mov_b32_e32 v126, v0
	v_mov_b32_e32 v127, v0
	.p2align	6

.LBB0_458:
	s_ashr_i32 s13, s12, 31
	s_lshl_b64 s[20:21], s[12:13], 20
	s_add_u32 s20, s3, s20
	s_addc_u32 s21, s22, s21
	s_and_b64 s[24:25], s[4:5], exec
	s_cselect_b32 s13, s21, s27
	s_cselect_b32 s50, s20, s26
	s_ashr_i32 s11, s10, 31
	s_lshl_b64 s[24:25], s[10:11], 20
	v_readlane_b32 s11, v234, 53
	s_add_u32 s24, s11, s24
	s_addc_u32 s25, s89, s25
	s_and_b64 s[30:31], s[4:5], exec
	s_cselect_b32 s11, s25, s29
	s_cselect_b32 s51, s24, s28
	s_add_u32 s26, s26, 0x80080
	s_addc_u32 s27, s27, 0
	s_add_u32 s52, s28, 0x100
	v_mov_b32_e32 v0, 0
	s_addc_u32 s53, s29, 0
	s_mov_b32 s54, -2
	v_mov_b32_e32 v1, v0
	v_mov_b32_e32 v2, v0
	v_mov_b32_e32 v3, v0
	v_mov_b32_e32 v4, v0
	v_mov_b32_e32 v5, v0
	v_mov_b32_e32 v6, v0
	v_mov_b32_e32 v7, v0
	v_mov_b32_e32 v8, v0
	v_mov_b32_e32 v9, v0
	v_mov_b32_e32 v10, v0
	v_mov_b32_e32 v11, v0
	v_mov_b32_e32 v12, v0
	v_mov_b32_e32 v13, v0
	v_mov_b32_e32 v14, v0
	v_mov_b32_e32 v15, v0
	v_mov_b32_e32 v24, v0
	v_mov_b32_e32 v25, v0
	v_mov_b32_e32 v26, v0
	v_mov_b32_e32 v27, v0
	v_mov_b32_e32 v28, v0
	v_mov_b32_e32 v29, v0
	v_mov_b32_e32 v30, v0
	v_mov_b32_e32 v31, v0
	v_mov_b32_e32 v40, v0
	v_mov_b32_e32 v41, v0
	v_mov_b32_e32 v42, v0
	v_mov_b32_e32 v43, v0
	v_mov_b32_e32 v44, v0
	v_mov_b32_e32 v45, v0
	v_mov_b32_e32 v46, v0
	v_mov_b32_e32 v47, v0
	v_mov_b32_e32 v16, v0
	v_mov_b32_e32 v17, v0
	v_mov_b32_e32 v18, v0
	v_mov_b32_e32 v19, v0
	v_mov_b32_e32 v20, v0
	v_mov_b32_e32 v21, v0
	v_mov_b32_e32 v22, v0
	v_mov_b32_e32 v23, v0
	v_mov_b32_e32 v32, v0
	v_mov_b32_e32 v33, v0
	v_mov_b32_e32 v34, v0
	v_mov_b32_e32 v35, v0
	v_mov_b32_e32 v36, v0
	v_mov_b32_e32 v37, v0
	v_mov_b32_e32 v38, v0
	v_mov_b32_e32 v39, v0
	v_mov_b32_e32 v48, v0
	v_mov_b32_e32 v49, v0
	v_mov_b32_e32 v50, v0
	v_mov_b32_e32 v51, v0
	v_mov_b32_e32 v52, v0
	v_mov_b32_e32 v53, v0
	v_mov_b32_e32 v54, v0
	v_mov_b32_e32 v55, v0
	v_mov_b32_e32 v56, v0
	v_mov_b32_e32 v57, v0
	v_mov_b32_e32 v58, v0
	v_mov_b32_e32 v59, v0
	v_mov_b32_e32 v60, v0
	v_mov_b32_e32 v61, v0
	v_mov_b32_e32 v62, v0
	v_mov_b32_e32 v63, v0
	v_mov_b32_e32 v64, v0
	v_mov_b32_e32 v65, v0
	v_mov_b32_e32 v66, v0
	v_mov_b32_e32 v67, v0
	v_mov_b32_e32 v68, v0
	v_mov_b32_e32 v69, v0
	v_mov_b32_e32 v70, v0
	v_mov_b32_e32 v71, v0
	v_mov_b32_e32 v72, v0
	v_mov_b32_e32 v73, v0
	v_mov_b32_e32 v74, v0
	v_mov_b32_e32 v75, v0
	v_mov_b32_e32 v76, v0
	v_mov_b32_e32 v77, v0
	v_mov_b32_e32 v78, v0
	v_mov_b32_e32 v79, v0
	v_mov_b32_e32 v88, v0
	v_mov_b32_e32 v89, v0
	v_mov_b32_e32 v90, v0
	v_mov_b32_e32 v91, v0
	v_mov_b32_e32 v92, v0
	v_mov_b32_e32 v93, v0
	v_mov_b32_e32 v94, v0
	v_mov_b32_e32 v95, v0
	v_mov_b32_e32 v104, v0
	v_mov_b32_e32 v105, v0
	v_mov_b32_e32 v106, v0
	v_mov_b32_e32 v107, v0
	v_mov_b32_e32 v108, v0
	v_mov_b32_e32 v109, v0
	v_mov_b32_e32 v110, v0
	v_mov_b32_e32 v111, v0
	v_mov_b32_e32 v80, v0
	v_mov_b32_e32 v81, v0
	v_mov_b32_e32 v82, v0
	v_mov_b32_e32 v83, v0
	v_mov_b32_e32 v84, v0
	v_mov_b32_e32 v85, v0
	v_mov_b32_e32 v86, v0
	v_mov_b32_e32 v87, v0
	v_mov_b32_e32 v96, v0
	v_mov_b32_e32 v97, v0
	v_mov_b32_e32 v98, v0
	v_mov_b32_e32 v99, v0
	v_mov_b32_e32 v100, v0
	v_mov_b32_e32 v101, v0
	v_mov_b32_e32 v102, v0
	v_mov_b32_e32 v103, v0
	v_mov_b32_e32 v112, v0
	v_mov_b32_e32 v113, v0
	v_mov_b32_e32 v114, v0
	v_mov_b32_e32 v115, v0
	v_mov_b32_e32 v116, v0
	v_mov_b32_e32 v117, v0
	v_mov_b32_e32 v118, v0
	v_mov_b32_e32 v119, v0
	v_mov_b32_e32 v120, v0
	v_mov_b32_e32 v121, v0
	v_mov_b32_e32 v122, v0
	v_mov_b32_e32 v123, v0
	v_mov_b32_e32 v124, v0
	v_mov_b32_e32 v125, v0
	v_mov_b32_e32 v126, v0
	v_mov_b32_e32 v127, v0
	.p2align	6

.LBB0_584:
	s_ashr_i32 s21, s20, 31
	s_lshl_b64 s[24:25], s[20:21], 18
	s_add_u32 s24, s57, s24
	s_addc_u32 s25, s62, s25
	s_and_b64 s[26:27], s[4:5], exec
	s_cselect_b32 s21, s25, s31
	s_cselect_b32 s53, s24, s30
	s_ashr_i32 s15, s14, 31
	s_lshl_b64 s[26:27], s[14:15], 18
	v_readlane_b32 s15, v234, 45
	s_add_u32 s26, s15, s26
	v_readlane_b32 s15, v234, 46
	s_addc_u32 s27, s15, s27
	s_and_b64 s[36:37], s[4:5], exec
	s_cselect_b32 s15, s27, s35
	s_cselect_b32 s54, s26, s34
	s_add_u32 s30, s30, 0x20080
	s_addc_u32 s31, s31, 0
	s_add_u32 s55, s34, 0x100
	v_mov_b32_e32 v32, 0
	s_addc_u32 s63, s35, 0
	s_mov_b32 s64, -2
	v_mov_b32_e32 v33, v32
	v_mov_b32_e32 v34, v32
	v_mov_b32_e32 v35, v32
	v_mov_b32_e32 v40, v32
	v_mov_b32_e32 v41, v32
	v_mov_b32_e32 v42, v32
	v_mov_b32_e32 v43, v32
	v_mov_b32_e32 v48, v32
	v_mov_b32_e32 v49, v32
	v_mov_b32_e32 v50, v32
	v_mov_b32_e32 v51, v32
	v_mov_b32_e32 v56, v32
	v_mov_b32_e32 v57, v32
	v_mov_b32_e32 v58, v32
	v_mov_b32_e32 v59, v32
	v_mov_b32_e32 v64, v32
	v_mov_b32_e32 v65, v32
	v_mov_b32_e32 v66, v32
	v_mov_b32_e32 v67, v32
	v_mov_b32_e32 v72, v32
	v_mov_b32_e32 v73, v32
	v_mov_b32_e32 v74, v32
	v_mov_b32_e32 v75, v32
	v_mov_b32_e32 v80, v32
	v_mov_b32_e32 v81, v32
	v_mov_b32_e32 v82, v32
	v_mov_b32_e32 v83, v32
	v_mov_b32_e32 v88, v32
	v_mov_b32_e32 v89, v32
	v_mov_b32_e32 v90, v32
	v_mov_b32_e32 v91, v32
	v_mov_b32_e32 v36, v32
	v_mov_b32_e32 v37, v32
	v_mov_b32_e32 v38, v32
	v_mov_b32_e32 v39, v32
	v_mov_b32_e32 v44, v32
	v_mov_b32_e32 v45, v32
	v_mov_b32_e32 v46, v32
	v_mov_b32_e32 v47, v32
	v_mov_b32_e32 v52, v32
	v_mov_b32_e32 v53, v32
	v_mov_b32_e32 v54, v32
	v_mov_b32_e32 v55, v32
	v_mov_b32_e32 v60, v32
	v_mov_b32_e32 v61, v32
	v_mov_b32_e32 v62, v32
	v_mov_b32_e32 v63, v32
	v_mov_b32_e32 v68, v32
	v_mov_b32_e32 v69, v32
	v_mov_b32_e32 v70, v32
	v_mov_b32_e32 v71, v32
	v_mov_b32_e32 v76, v32
	v_mov_b32_e32 v77, v32
	v_mov_b32_e32 v78, v32
	v_mov_b32_e32 v79, v32
	v_mov_b32_e32 v84, v32
	v_mov_b32_e32 v85, v32
	v_mov_b32_e32 v86, v32
	v_mov_b32_e32 v87, v32
	v_mov_b32_e32 v92, v32
	v_mov_b32_e32 v93, v32
	v_mov_b32_e32 v94, v32
	v_mov_b32_e32 v95, v32
	v_mov_b32_e32 v96, v32
	v_mov_b32_e32 v97, v32
	v_mov_b32_e32 v98, v32
	v_mov_b32_e32 v99, v32
	v_mov_b32_e32 v104, v32
	v_mov_b32_e32 v105, v32
	v_mov_b32_e32 v106, v32
	v_mov_b32_e32 v107, v32
	v_mov_b32_e32 v112, v32
	v_mov_b32_e32 v113, v32
	v_mov_b32_e32 v114, v32
	v_mov_b32_e32 v115, v32
	v_mov_b32_e32 v120, v32
	v_mov_b32_e32 v121, v32
	v_mov_b32_e32 v122, v32
	v_mov_b32_e32 v123, v32
	v_mov_b32_e32 v128, v32
	v_mov_b32_e32 v129, v32
	v_mov_b32_e32 v130, v32
	v_mov_b32_e32 v131, v32
	v_mov_b32_e32 v136, v32
	v_mov_b32_e32 v137, v32
	v_mov_b32_e32 v138, v32
	v_mov_b32_e32 v139, v32
	v_mov_b32_e32 v144, v32
	v_mov_b32_e32 v145, v32
	v_mov_b32_e32 v146, v32
	v_mov_b32_e32 v147, v32
	v_mov_b32_e32 v152, v32
	v_mov_b32_e32 v153, v32
	v_mov_b32_e32 v154, v32
	v_mov_b32_e32 v155, v32
	v_mov_b32_e32 v100, v32
	v_mov_b32_e32 v101, v32
	v_mov_b32_e32 v102, v32
	v_mov_b32_e32 v103, v32
	v_mov_b32_e32 v108, v32
	v_mov_b32_e32 v109, v32
	v_mov_b32_e32 v110, v32
	v_mov_b32_e32 v111, v32
	v_mov_b32_e32 v116, v32
	v_mov_b32_e32 v117, v32
	v_mov_b32_e32 v118, v32
	v_mov_b32_e32 v119, v32
	v_mov_b32_e32 v124, v32
	v_mov_b32_e32 v125, v32
	v_mov_b32_e32 v126, v32
	v_mov_b32_e32 v127, v32
	v_mov_b32_e32 v132, v32
	v_mov_b32_e32 v133, v32
	v_mov_b32_e32 v134, v32
	v_mov_b32_e32 v135, v32
	v_mov_b32_e32 v140, v32
	v_mov_b32_e32 v141, v32
	v_mov_b32_e32 v142, v32
	v_mov_b32_e32 v143, v32
	v_mov_b32_e32 v148, v32
	v_mov_b32_e32 v149, v32
	v_mov_b32_e32 v150, v32
	v_mov_b32_e32 v151, v32
	v_mov_b32_e32 v156, v32
	v_mov_b32_e32 v157, v32
	v_mov_b32_e32 v158, v32
	v_mov_b32_e32 v159, v32
	.p2align	6

.LBB0_661:
	s_add_u32 s20, s20, 0x58080
	s_addc_u32 s21, s21, 0
	s_add_u32 s45, s24, 0x100
	v_mov_b32_e32 v32, 0
	s_addc_u32 s47, s25, 0
	s_mov_b32 s48, -2
	v_mov_b32_e32 v33, v32
	v_mov_b32_e32 v34, v32
	v_mov_b32_e32 v35, v32
	v_mov_b32_e32 v36, v32
	v_mov_b32_e32 v37, v32
	v_mov_b32_e32 v38, v32
	v_mov_b32_e32 v39, v32
	v_mov_b32_e32 v40, v32
	v_mov_b32_e32 v41, v32
	v_mov_b32_e32 v42, v32
	v_mov_b32_e32 v43, v32
	v_mov_b32_e32 v48, v32
	v_mov_b32_e32 v49, v32
	v_mov_b32_e32 v50, v32
	v_mov_b32_e32 v51, v32
	v_mov_b32_e32 v56, v32
	v_mov_b32_e32 v57, v32
	v_mov_b32_e32 v58, v32
	v_mov_b32_e32 v59, v32
	v_mov_b32_e32 v64, v32
	v_mov_b32_e32 v65, v32
	v_mov_b32_e32 v66, v32
	v_mov_b32_e32 v67, v32
	v_mov_b32_e32 v72, v32
	v_mov_b32_e32 v73, v32
	v_mov_b32_e32 v74, v32
	v_mov_b32_e32 v75, v32
	v_mov_b32_e32 v80, v32
	v_mov_b32_e32 v81, v32
	v_mov_b32_e32 v82, v32
	v_mov_b32_e32 v83, v32
	v_mov_b32_e32 v44, v32
	v_mov_b32_e32 v45, v32
	v_mov_b32_e32 v46, v32
	v_mov_b32_e32 v47, v32
	v_mov_b32_e32 v52, v32
	v_mov_b32_e32 v53, v32
	v_mov_b32_e32 v54, v32
	v_mov_b32_e32 v55, v32
	v_mov_b32_e32 v60, v32
	v_mov_b32_e32 v61, v32
	v_mov_b32_e32 v62, v32
	v_mov_b32_e32 v63, v32
	v_mov_b32_e32 v68, v32
	v_mov_b32_e32 v69, v32
	v_mov_b32_e32 v70, v32
	v_mov_b32_e32 v71, v32
	v_mov_b32_e32 v76, v32
	v_mov_b32_e32 v77, v32
	v_mov_b32_e32 v78, v32
	v_mov_b32_e32 v79, v32
	v_mov_b32_e32 v84, v32
	v_mov_b32_e32 v85, v32
	v_mov_b32_e32 v86, v32
	v_mov_b32_e32 v87, v32
	v_mov_b32_e32 v88, v32
	v_mov_b32_e32 v89, v32
	v_mov_b32_e32 v90, v32
	v_mov_b32_e32 v91, v32
	v_mov_b32_e32 v92, v32
	v_mov_b32_e32 v93, v32
	v_mov_b32_e32 v94, v32
	v_mov_b32_e32 v95, v32
	v_mov_b32_e32 v96, v32
	v_mov_b32_e32 v97, v32
	v_mov_b32_e32 v98, v32
	v_mov_b32_e32 v99, v32
	v_mov_b32_e32 v100, v32
	v_mov_b32_e32 v101, v32
	v_mov_b32_e32 v102, v32
	v_mov_b32_e32 v103, v32
	v_mov_b32_e32 v104, v32
	v_mov_b32_e32 v105, v32
	v_mov_b32_e32 v106, v32
	v_mov_b32_e32 v107, v32
	v_mov_b32_e32 v112, v32
	v_mov_b32_e32 v113, v32
	v_mov_b32_e32 v114, v32
	v_mov_b32_e32 v115, v32
	v_mov_b32_e32 v120, v32
	v_mov_b32_e32 v121, v32
	v_mov_b32_e32 v122, v32
	v_mov_b32_e32 v123, v32
	v_mov_b32_e32 v128, v32
	v_mov_b32_e32 v129, v32
	v_mov_b32_e32 v130, v32
	v_mov_b32_e32 v131, v32
	v_mov_b32_e32 v136, v32
	v_mov_b32_e32 v137, v32
	v_mov_b32_e32 v138, v32
	v_mov_b32_e32 v139, v32
	v_mov_b32_e32 v144, v32
	v_mov_b32_e32 v145, v32
	v_mov_b32_e32 v146, v32
	v_mov_b32_e32 v147, v32
	v_mov_b32_e32 v108, v32
	v_mov_b32_e32 v109, v32
	v_mov_b32_e32 v110, v32
	v_mov_b32_e32 v111, v32
	v_mov_b32_e32 v116, v32
	v_mov_b32_e32 v117, v32
	v_mov_b32_e32 v118, v32
	v_mov_b32_e32 v119, v32
	v_mov_b32_e32 v124, v32
	v_mov_b32_e32 v125, v32
	v_mov_b32_e32 v126, v32
	v_mov_b32_e32 v127, v32
	v_mov_b32_e32 v132, v32
	v_mov_b32_e32 v133, v32
	v_mov_b32_e32 v134, v32
	v_mov_b32_e32 v135, v32
	v_mov_b32_e32 v140, v32
	v_mov_b32_e32 v141, v32
	v_mov_b32_e32 v142, v32
	v_mov_b32_e32 v143, v32
	v_mov_b32_e32 v148, v32
	v_mov_b32_e32 v149, v32
	v_mov_b32_e32 v150, v32
	v_mov_b32_e32 v151, v32
	v_mov_b32_e32 v152, v32
	v_mov_b32_e32 v153, v32
	v_mov_b32_e32 v154, v32
	v_mov_b32_e32 v155, v32
	v_mov_b32_e32 v156, v32
	v_mov_b32_e32 v157, v32
	v_mov_b32_e32 v158, v32
	v_mov_b32_e32 v159, v32
	.p2align	6

.LBB0_791:
	s_ashr_i32 s13, s12, 31
	s_lshl_b64 s[18:19], s[12:13], 19
	s_add_u32 s18, s57, s18
	s_addc_u32 s19, s62, s19
	s_and_b64 s[20:21], s[4:5], exec
	s_cselect_b32 s13, s19, s25
	s_cselect_b32 s44, s18, s24
	s_ashr_i32 s11, s10, 31
	s_lshl_b64 s[20:21], s[10:11], 19
	v_readlane_b32 s11, v234, 51
	s_add_u32 s20, s11, s20
	v_readlane_b32 s11, v234, 52
	s_addc_u32 s21, s11, s21
	s_and_b64 s[28:29], s[4:5], exec
	s_cselect_b32 s11, s21, s27
	s_cselect_b32 s45, s20, s26
	s_add_u32 s24, s24, 0x40080
	s_addc_u32 s25, s25, 0
	s_add_u32 s47, s26, 0x100
	v_mov_b32_e32 v0, 0
	s_addc_u32 s48, s27, 0
	s_mov_b32 s49, -2
	v_mov_b32_e32 v1, v0
	v_mov_b32_e32 v2, v0
	v_mov_b32_e32 v3, v0
	v_mov_b32_e32 v4, v0
	v_mov_b32_e32 v5, v0
	v_mov_b32_e32 v6, v0
	v_mov_b32_e32 v7, v0
	v_mov_b32_e32 v8, v0
	v_mov_b32_e32 v9, v0
	v_mov_b32_e32 v10, v0
	v_mov_b32_e32 v11, v0
	v_mov_b32_e32 v12, v0
	v_mov_b32_e32 v13, v0
	v_mov_b32_e32 v14, v0
	v_mov_b32_e32 v15, v0
	v_mov_b32_e32 v24, v0
	v_mov_b32_e32 v25, v0
	v_mov_b32_e32 v26, v0
	v_mov_b32_e32 v27, v0
	v_mov_b32_e32 v28, v0
	v_mov_b32_e32 v29, v0
	v_mov_b32_e32 v30, v0
	v_mov_b32_e32 v31, v0
	v_mov_b32_e32 v40, v0
	v_mov_b32_e32 v41, v0
	v_mov_b32_e32 v42, v0
	v_mov_b32_e32 v43, v0
	v_mov_b32_e32 v44, v0
	v_mov_b32_e32 v45, v0
	v_mov_b32_e32 v46, v0
	v_mov_b32_e32 v47, v0
	v_mov_b32_e32 v16, v0
	v_mov_b32_e32 v17, v0
	v_mov_b32_e32 v18, v0
	v_mov_b32_e32 v19, v0
	v_mov_b32_e32 v20, v0
	v_mov_b32_e32 v21, v0
	v_mov_b32_e32 v22, v0
	v_mov_b32_e32 v23, v0
	v_mov_b32_e32 v32, v0
	v_mov_b32_e32 v33, v0
	v_mov_b32_e32 v34, v0
	v_mov_b32_e32 v35, v0
	v_mov_b32_e32 v36, v0
	v_mov_b32_e32 v37, v0
	v_mov_b32_e32 v38, v0
	v_mov_b32_e32 v39, v0
	v_mov_b32_e32 v48, v0
	v_mov_b32_e32 v49, v0
	v_mov_b32_e32 v50, v0
	v_mov_b32_e32 v51, v0
	v_mov_b32_e32 v52, v0
	v_mov_b32_e32 v53, v0
	v_mov_b32_e32 v54, v0
	v_mov_b32_e32 v55, v0
	v_mov_b32_e32 v56, v0
	v_mov_b32_e32 v57, v0
	v_mov_b32_e32 v58, v0
	v_mov_b32_e32 v59, v0
	v_mov_b32_e32 v60, v0
	v_mov_b32_e32 v61, v0
	v_mov_b32_e32 v62, v0
	v_mov_b32_e32 v63, v0
	v_mov_b32_e32 v64, v0
	v_mov_b32_e32 v65, v0
	v_mov_b32_e32 v66, v0
	v_mov_b32_e32 v67, v0
	v_mov_b32_e32 v68, v0
	v_mov_b32_e32 v69, v0
	v_mov_b32_e32 v70, v0
	v_mov_b32_e32 v71, v0
	v_mov_b32_e32 v72, v0
	v_mov_b32_e32 v73, v0
	v_mov_b32_e32 v74, v0
	v_mov_b32_e32 v75, v0
	v_mov_b32_e32 v76, v0
	v_mov_b32_e32 v77, v0
	v_mov_b32_e32 v78, v0
	v_mov_b32_e32 v79, v0
	v_mov_b32_e32 v88, v0
	v_mov_b32_e32 v89, v0
	v_mov_b32_e32 v90, v0
	v_mov_b32_e32 v91, v0
	v_mov_b32_e32 v92, v0
	v_mov_b32_e32 v93, v0
	v_mov_b32_e32 v94, v0
	v_mov_b32_e32 v95, v0
	v_mov_b32_e32 v104, v0
	v_mov_b32_e32 v105, v0
	v_mov_b32_e32 v106, v0
	v_mov_b32_e32 v107, v0
	v_mov_b32_e32 v108, v0
	v_mov_b32_e32 v109, v0
	v_mov_b32_e32 v110, v0
	v_mov_b32_e32 v111, v0
	v_mov_b32_e32 v80, v0
	v_mov_b32_e32 v81, v0
	v_mov_b32_e32 v82, v0
	v_mov_b32_e32 v83, v0
	v_mov_b32_e32 v84, v0
	v_mov_b32_e32 v85, v0
	v_mov_b32_e32 v86, v0
	v_mov_b32_e32 v87, v0
	v_mov_b32_e32 v96, v0
	v_mov_b32_e32 v97, v0
	v_mov_b32_e32 v98, v0
	v_mov_b32_e32 v99, v0
	v_mov_b32_e32 v100, v0
	v_mov_b32_e32 v101, v0
	v_mov_b32_e32 v102, v0
	v_mov_b32_e32 v103, v0
	v_mov_b32_e32 v112, v0
	v_mov_b32_e32 v113, v0
	v_mov_b32_e32 v114, v0
	v_mov_b32_e32 v115, v0
	v_mov_b32_e32 v116, v0
	v_mov_b32_e32 v117, v0
	v_mov_b32_e32 v118, v0
	v_mov_b32_e32 v119, v0
	v_mov_b32_e32 v120, v0
	v_mov_b32_e32 v121, v0
	v_mov_b32_e32 v122, v0
	v_mov_b32_e32 v123, v0
	v_mov_b32_e32 v124, v0
	v_mov_b32_e32 v125, v0
	v_mov_b32_e32 v126, v0
	v_mov_b32_e32 v127, v0
	.p2align	6

.LBB0_811:
	s_ashr_i32 s13, s12, 31
	s_lshl_b64 s[18:19], s[12:13], 19
	s_add_u32 s18, s81, s18
	v_readlane_b32 s11, v234, 50
	s_addc_u32 s19, s11, s19
	s_and_b64 s[20:21], s[4:5], exec
	s_cselect_b32 s13, s19, s25
	s_cselect_b32 s44, s18, s24
	s_ashr_i32 s11, s10, 31
	s_lshl_b64 s[20:21], s[10:11], 19
	s_add_u32 s20, s57, s20
	s_addc_u32 s21, s62, s21
	s_and_b64 s[28:29], s[4:5], exec
	s_cselect_b32 s11, s21, s27
	s_cselect_b32 s45, s20, s26
	s_add_u32 s24, s24, 0x40080
	s_addc_u32 s25, s25, 0
	s_add_u32 s47, s26, 0x100
	v_mov_b32_e32 v0, 0
	s_addc_u32 s48, s27, 0
	s_mov_b32 s49, -2
	v_mov_b32_e32 v1, v0
	v_mov_b32_e32 v2, v0
	v_mov_b32_e32 v3, v0
	v_mov_b32_e32 v4, v0
	v_mov_b32_e32 v5, v0
	v_mov_b32_e32 v6, v0
	v_mov_b32_e32 v7, v0
	v_mov_b32_e32 v8, v0
	v_mov_b32_e32 v9, v0
	v_mov_b32_e32 v10, v0
	v_mov_b32_e32 v11, v0
	v_mov_b32_e32 v12, v0
	v_mov_b32_e32 v13, v0
	v_mov_b32_e32 v14, v0
	v_mov_b32_e32 v15, v0
	v_mov_b32_e32 v24, v0
	v_mov_b32_e32 v25, v0
	v_mov_b32_e32 v26, v0
	v_mov_b32_e32 v27, v0
	v_mov_b32_e32 v28, v0
	v_mov_b32_e32 v29, v0
	v_mov_b32_e32 v30, v0
	v_mov_b32_e32 v31, v0
	v_mov_b32_e32 v40, v0
	v_mov_b32_e32 v41, v0
	v_mov_b32_e32 v42, v0
	v_mov_b32_e32 v43, v0
	v_mov_b32_e32 v44, v0
	v_mov_b32_e32 v45, v0
	v_mov_b32_e32 v46, v0
	v_mov_b32_e32 v47, v0
	v_mov_b32_e32 v16, v0
	v_mov_b32_e32 v17, v0
	v_mov_b32_e32 v18, v0
	v_mov_b32_e32 v19, v0
	v_mov_b32_e32 v20, v0
	v_mov_b32_e32 v21, v0
	v_mov_b32_e32 v22, v0
	v_mov_b32_e32 v23, v0
	v_mov_b32_e32 v32, v0
	v_mov_b32_e32 v33, v0
	v_mov_b32_e32 v34, v0
	v_mov_b32_e32 v35, v0
	v_mov_b32_e32 v36, v0
	v_mov_b32_e32 v37, v0
	v_mov_b32_e32 v38, v0
	v_mov_b32_e32 v39, v0
	v_mov_b32_e32 v48, v0
	v_mov_b32_e32 v49, v0
	v_mov_b32_e32 v50, v0
	v_mov_b32_e32 v51, v0
	v_mov_b32_e32 v52, v0
	v_mov_b32_e32 v53, v0
	v_mov_b32_e32 v54, v0
	v_mov_b32_e32 v55, v0
	v_mov_b32_e32 v56, v0
	v_mov_b32_e32 v57, v0
	v_mov_b32_e32 v58, v0
	v_mov_b32_e32 v59, v0
	v_mov_b32_e32 v60, v0
	v_mov_b32_e32 v61, v0
	v_mov_b32_e32 v62, v0
	v_mov_b32_e32 v63, v0
	v_mov_b32_e32 v64, v0
	v_mov_b32_e32 v65, v0
	v_mov_b32_e32 v66, v0
	v_mov_b32_e32 v67, v0
	v_mov_b32_e32 v68, v0
	v_mov_b32_e32 v69, v0
	v_mov_b32_e32 v70, v0
	v_mov_b32_e32 v71, v0
	v_mov_b32_e32 v72, v0
	v_mov_b32_e32 v73, v0
	v_mov_b32_e32 v74, v0
	v_mov_b32_e32 v75, v0
	v_mov_b32_e32 v76, v0
	v_mov_b32_e32 v77, v0
	v_mov_b32_e32 v78, v0
	v_mov_b32_e32 v79, v0
	v_mov_b32_e32 v88, v0
	v_mov_b32_e32 v89, v0
	v_mov_b32_e32 v90, v0
	v_mov_b32_e32 v91, v0
	v_mov_b32_e32 v92, v0
	v_mov_b32_e32 v93, v0
	v_mov_b32_e32 v94, v0
	v_mov_b32_e32 v95, v0
	v_mov_b32_e32 v104, v0
	v_mov_b32_e32 v105, v0
	v_mov_b32_e32 v106, v0
	v_mov_b32_e32 v107, v0
	v_mov_b32_e32 v108, v0
	v_mov_b32_e32 v109, v0
	v_mov_b32_e32 v110, v0
	v_mov_b32_e32 v111, v0
	v_mov_b32_e32 v80, v0
	v_mov_b32_e32 v81, v0
	v_mov_b32_e32 v82, v0
	v_mov_b32_e32 v83, v0
	v_mov_b32_e32 v84, v0
	v_mov_b32_e32 v85, v0
	v_mov_b32_e32 v86, v0
	v_mov_b32_e32 v87, v0
	v_mov_b32_e32 v96, v0
	v_mov_b32_e32 v97, v0
	v_mov_b32_e32 v98, v0
	v_mov_b32_e32 v99, v0
	v_mov_b32_e32 v100, v0
	v_mov_b32_e32 v101, v0
	v_mov_b32_e32 v102, v0
	v_mov_b32_e32 v103, v0
	v_mov_b32_e32 v112, v0
	v_mov_b32_e32 v113, v0
	v_mov_b32_e32 v114, v0
	v_mov_b32_e32 v115, v0
	v_mov_b32_e32 v116, v0
	v_mov_b32_e32 v117, v0
	v_mov_b32_e32 v118, v0
	v_mov_b32_e32 v119, v0
	v_mov_b32_e32 v120, v0
	v_mov_b32_e32 v121, v0
	v_mov_b32_e32 v122, v0
	v_mov_b32_e32 v123, v0
	v_mov_b32_e32 v124, v0
	v_mov_b32_e32 v125, v0
	v_mov_b32_e32 v126, v0
	v_mov_b32_e32 v127, v0
	.p2align	6

.LBB0_992:
	s_ashr_i32 s17, s16, 31
	s_lshl_b64 s[20:21], s[16:17], 19
	s_add_u32 s20, s68, s20
	s_addc_u32 s21, s69, s21
	s_and_b64 s[24:25], s[4:5], exec
	s_cselect_b32 s17, s21, s27
	s_cselect_b32 s50, s20, s26
	s_ashr_i32 s15, s14, 31
	s_lshl_b64 s[24:25], s[14:15], 19
	v_readlane_b32 s15, v234, 47
	s_add_u32 s24, s15, s24
	v_readlane_b32 s15, v234, 48
	s_addc_u32 s25, s15, s25
	s_and_b64 s[30:31], s[4:5], exec
	s_cselect_b32 s15, s25, s29
	s_cselect_b32 s51, s24, s28
	s_add_u32 s26, s26, 0x40080
	s_addc_u32 s27, s27, 0
	s_add_u32 s52, s28, 0x100
	v_mov_b32_e32 v0, 0
	s_addc_u32 s53, s29, 0
	s_mov_b32 s54, -2
	v_mov_b32_e32 v1, v0
	v_mov_b32_e32 v2, v0
	v_mov_b32_e32 v3, v0
	v_mov_b32_e32 v4, v0
	v_mov_b32_e32 v5, v0
	v_mov_b32_e32 v6, v0
	v_mov_b32_e32 v7, v0
	v_mov_b32_e32 v8, v0
	v_mov_b32_e32 v9, v0
	v_mov_b32_e32 v10, v0
	v_mov_b32_e32 v11, v0
	v_mov_b32_e32 v12, v0
	v_mov_b32_e32 v13, v0
	v_mov_b32_e32 v14, v0
	v_mov_b32_e32 v15, v0
	v_mov_b32_e32 v24, v0
	v_mov_b32_e32 v25, v0
	v_mov_b32_e32 v26, v0
	v_mov_b32_e32 v27, v0
	v_mov_b32_e32 v28, v0
	v_mov_b32_e32 v29, v0
	v_mov_b32_e32 v30, v0
	v_mov_b32_e32 v31, v0
	v_mov_b32_e32 v40, v0
	v_mov_b32_e32 v41, v0
	v_mov_b32_e32 v42, v0
	v_mov_b32_e32 v43, v0
	v_mov_b32_e32 v44, v0
	v_mov_b32_e32 v45, v0
	v_mov_b32_e32 v46, v0
	v_mov_b32_e32 v47, v0
	v_mov_b32_e32 v16, v0
	v_mov_b32_e32 v17, v0
	v_mov_b32_e32 v18, v0
	v_mov_b32_e32 v19, v0
	v_mov_b32_e32 v20, v0
	v_mov_b32_e32 v21, v0
	v_mov_b32_e32 v22, v0
	v_mov_b32_e32 v23, v0
	v_mov_b32_e32 v32, v0
	v_mov_b32_e32 v33, v0
	v_mov_b32_e32 v34, v0
	v_mov_b32_e32 v35, v0
	v_mov_b32_e32 v36, v0
	v_mov_b32_e32 v37, v0
	v_mov_b32_e32 v38, v0
	v_mov_b32_e32 v39, v0
	v_mov_b32_e32 v48, v0
	v_mov_b32_e32 v49, v0
	v_mov_b32_e32 v50, v0
	v_mov_b32_e32 v51, v0
	v_mov_b32_e32 v52, v0
	v_mov_b32_e32 v53, v0
	v_mov_b32_e32 v54, v0
	v_mov_b32_e32 v55, v0
	v_mov_b32_e32 v56, v0
	v_mov_b32_e32 v57, v0
	v_mov_b32_e32 v58, v0
	v_mov_b32_e32 v59, v0
	v_mov_b32_e32 v60, v0
	v_mov_b32_e32 v61, v0
	v_mov_b32_e32 v62, v0
	v_mov_b32_e32 v63, v0
	v_mov_b32_e32 v64, v0
	v_mov_b32_e32 v65, v0
	v_mov_b32_e32 v66, v0
	v_mov_b32_e32 v67, v0
	v_mov_b32_e32 v68, v0
	v_mov_b32_e32 v69, v0
	v_mov_b32_e32 v70, v0
	v_mov_b32_e32 v71, v0
	v_mov_b32_e32 v72, v0
	v_mov_b32_e32 v73, v0
	v_mov_b32_e32 v74, v0
	v_mov_b32_e32 v75, v0
	v_mov_b32_e32 v76, v0
	v_mov_b32_e32 v77, v0
	v_mov_b32_e32 v78, v0
	v_mov_b32_e32 v79, v0
	v_mov_b32_e32 v88, v0
	v_mov_b32_e32 v89, v0
	v_mov_b32_e32 v90, v0
	v_mov_b32_e32 v91, v0
	v_mov_b32_e32 v92, v0
	v_mov_b32_e32 v93, v0
	v_mov_b32_e32 v94, v0
	v_mov_b32_e32 v95, v0
	v_mov_b32_e32 v104, v0
	v_mov_b32_e32 v105, v0
	v_mov_b32_e32 v106, v0
	v_mov_b32_e32 v107, v0
	v_mov_b32_e32 v108, v0
	v_mov_b32_e32 v109, v0
	v_mov_b32_e32 v110, v0
	v_mov_b32_e32 v111, v0
	v_mov_b32_e32 v80, v0
	v_mov_b32_e32 v81, v0
	v_mov_b32_e32 v82, v0
	v_mov_b32_e32 v83, v0
	v_mov_b32_e32 v84, v0
	v_mov_b32_e32 v85, v0
	v_mov_b32_e32 v86, v0
	v_mov_b32_e32 v87, v0
	v_mov_b32_e32 v96, v0
	v_mov_b32_e32 v97, v0
	v_mov_b32_e32 v98, v0
	v_mov_b32_e32 v99, v0
	v_mov_b32_e32 v100, v0
	v_mov_b32_e32 v101, v0
	v_mov_b32_e32 v102, v0
	v_mov_b32_e32 v103, v0
	v_mov_b32_e32 v112, v0
	v_mov_b32_e32 v113, v0
	v_mov_b32_e32 v114, v0
	v_mov_b32_e32 v115, v0
	v_mov_b32_e32 v116, v0
	v_mov_b32_e32 v117, v0
	v_mov_b32_e32 v118, v0
	v_mov_b32_e32 v119, v0
	v_mov_b32_e32 v120, v0
	v_mov_b32_e32 v121, v0
	v_mov_b32_e32 v122, v0
	v_mov_b32_e32 v123, v0
	v_mov_b32_e32 v124, v0
	v_mov_b32_e32 v125, v0
	v_mov_b32_e32 v126, v0
	v_mov_b32_e32 v127, v0
	.p2align	6

.LBB0_1271:
	s_lshl_b64 s[18:19], s[14:15], 18
	s_add_u32 s18, s68, s18
	s_addc_u32 s19, s69, s19
	s_and_b64 s[20:21], exec, s[0:1]
	s_cselect_b32 s15, s19, s29
	s_cselect_b32 s57, s18, s28
	s_ashr_i32 s17, s16, 31
	s_lshl_b64 s[20:21], s[16:17], 18
	s_add_u32 s20, s76, s20
	s_addc_u32 s21, s77, s21
	s_and_b64 s[34:35], exec, s[0:1]
	s_cselect_b32 s17, s21, s31
	s_cselect_b32 s62, s20, s30
	s_add_u32 s28, s28, 0x20080
	s_addc_u32 s29, s29, 0
	s_add_u32 s63, s30, 0x100
	v_mov_b32_e32 v32, 0
	s_addc_u32 s64, s31, 0
	s_mov_b32 s65, -2
	v_mov_b32_e32 v33, v32
	v_mov_b32_e32 v34, v32
	v_mov_b32_e32 v35, v32
	v_mov_b32_e32 v40, v32
	v_mov_b32_e32 v41, v32
	v_mov_b32_e32 v42, v32
	v_mov_b32_e32 v43, v32
	v_mov_b32_e32 v48, v32
	v_mov_b32_e32 v49, v32
	v_mov_b32_e32 v50, v32
	v_mov_b32_e32 v51, v32
	v_mov_b32_e32 v56, v32
	v_mov_b32_e32 v57, v32
	v_mov_b32_e32 v58, v32
	v_mov_b32_e32 v59, v32
	v_mov_b32_e32 v64, v32
	v_mov_b32_e32 v65, v32
	v_mov_b32_e32 v66, v32
	v_mov_b32_e32 v67, v32
	v_mov_b32_e32 v72, v32
	v_mov_b32_e32 v73, v32
	v_mov_b32_e32 v74, v32
	v_mov_b32_e32 v75, v32
	v_mov_b32_e32 v80, v32
	v_mov_b32_e32 v81, v32
	v_mov_b32_e32 v82, v32
	v_mov_b32_e32 v83, v32
	v_mov_b32_e32 v88, v32
	v_mov_b32_e32 v89, v32
	v_mov_b32_e32 v90, v32
	v_mov_b32_e32 v91, v32
	v_mov_b32_e32 v36, v32
	v_mov_b32_e32 v37, v32
	v_mov_b32_e32 v38, v32
	v_mov_b32_e32 v39, v32
	v_mov_b32_e32 v44, v32
	v_mov_b32_e32 v45, v32
	v_mov_b32_e32 v46, v32
	v_mov_b32_e32 v47, v32
	v_mov_b32_e32 v52, v32
	v_mov_b32_e32 v53, v32
	v_mov_b32_e32 v54, v32
	v_mov_b32_e32 v55, v32
	v_mov_b32_e32 v60, v32
	v_mov_b32_e32 v61, v32
	v_mov_b32_e32 v62, v32
	v_mov_b32_e32 v63, v32
	v_mov_b32_e32 v68, v32
	v_mov_b32_e32 v69, v32
	v_mov_b32_e32 v70, v32
	v_mov_b32_e32 v71, v32
	v_mov_b32_e32 v76, v32
	v_mov_b32_e32 v77, v32
	v_mov_b32_e32 v78, v32
	v_mov_b32_e32 v79, v32
	v_mov_b32_e32 v84, v32
	v_mov_b32_e32 v85, v32
	v_mov_b32_e32 v86, v32
	v_mov_b32_e32 v87, v32
	v_mov_b32_e32 v92, v32
	v_mov_b32_e32 v93, v32
	v_mov_b32_e32 v94, v32
	v_mov_b32_e32 v95, v32
	v_mov_b32_e32 v96, v32
	v_mov_b32_e32 v97, v32
	v_mov_b32_e32 v98, v32
	v_mov_b32_e32 v99, v32
	v_mov_b32_e32 v104, v32
	v_mov_b32_e32 v105, v32
	v_mov_b32_e32 v106, v32
	v_mov_b32_e32 v107, v32
	v_mov_b32_e32 v112, v32
	v_mov_b32_e32 v113, v32
	v_mov_b32_e32 v114, v32
	v_mov_b32_e32 v115, v32
	v_mov_b32_e32 v120, v32
	v_mov_b32_e32 v121, v32
	v_mov_b32_e32 v122, v32
	v_mov_b32_e32 v123, v32
	v_mov_b32_e32 v128, v32
	v_mov_b32_e32 v129, v32
	v_mov_b32_e32 v130, v32
	v_mov_b32_e32 v131, v32
	v_mov_b32_e32 v136, v32
	v_mov_b32_e32 v137, v32
	v_mov_b32_e32 v138, v32
	v_mov_b32_e32 v139, v32
	v_mov_b32_e32 v144, v32
	v_mov_b32_e32 v145, v32
	v_mov_b32_e32 v146, v32
	v_mov_b32_e32 v147, v32
	v_mov_b32_e32 v152, v32
	v_mov_b32_e32 v153, v32
	v_mov_b32_e32 v154, v32
	v_mov_b32_e32 v155, v32
	v_mov_b32_e32 v100, v32
	v_mov_b32_e32 v101, v32
	v_mov_b32_e32 v102, v32
	v_mov_b32_e32 v103, v32
	v_mov_b32_e32 v108, v32
	v_mov_b32_e32 v109, v32
	v_mov_b32_e32 v110, v32
	v_mov_b32_e32 v111, v32
	v_mov_b32_e32 v116, v32
	v_mov_b32_e32 v117, v32
	v_mov_b32_e32 v118, v32
	v_mov_b32_e32 v119, v32
	v_mov_b32_e32 v124, v32
	v_mov_b32_e32 v125, v32
	v_mov_b32_e32 v126, v32
	v_mov_b32_e32 v127, v32
	v_mov_b32_e32 v132, v32
	v_mov_b32_e32 v133, v32
	v_mov_b32_e32 v134, v32
	v_mov_b32_e32 v135, v32
	v_mov_b32_e32 v140, v32
	v_mov_b32_e32 v141, v32
	v_mov_b32_e32 v142, v32
	v_mov_b32_e32 v143, v32
	v_mov_b32_e32 v148, v32
	v_mov_b32_e32 v149, v32
	v_mov_b32_e32 v150, v32
	v_mov_b32_e32 v151, v32
	v_mov_b32_e32 v156, v32
	v_mov_b32_e32 v157, v32
	v_mov_b32_e32 v158, v32
	v_mov_b32_e32 v159, v32
	.p2align	6

.LBB0_1348:
	s_add_u32 s30, s30, 0x70080
	s_addc_u32 s31, s31, 0
	s_add_u32 s72, s34, 0x100
	v_mov_b32_e32 v32, 0
	s_addc_u32 s73, s35, 0
	s_mov_b32 s74, -2
	v_mov_b32_e32 v33, v32
	v_mov_b32_e32 v34, v32
	v_mov_b32_e32 v35, v32
	v_mov_b32_e32 v36, v32
	v_mov_b32_e32 v37, v32
	v_mov_b32_e32 v38, v32
	v_mov_b32_e32 v39, v32
	v_mov_b32_e32 v40, v32
	v_mov_b32_e32 v41, v32
	v_mov_b32_e32 v42, v32
	v_mov_b32_e32 v43, v32
	v_mov_b32_e32 v48, v32
	v_mov_b32_e32 v49, v32
	v_mov_b32_e32 v50, v32
	v_mov_b32_e32 v51, v32
	v_mov_b32_e32 v56, v32
	v_mov_b32_e32 v57, v32
	v_mov_b32_e32 v58, v32
	v_mov_b32_e32 v59, v32
	v_mov_b32_e32 v64, v32
	v_mov_b32_e32 v65, v32
	v_mov_b32_e32 v66, v32
	v_mov_b32_e32 v67, v32
	v_mov_b32_e32 v72, v32
	v_mov_b32_e32 v73, v32
	v_mov_b32_e32 v74, v32
	v_mov_b32_e32 v75, v32
	v_mov_b32_e32 v80, v32
	v_mov_b32_e32 v81, v32
	v_mov_b32_e32 v82, v32
	v_mov_b32_e32 v83, v32
	v_mov_b32_e32 v44, v32
	v_mov_b32_e32 v45, v32
	v_mov_b32_e32 v46, v32
	v_mov_b32_e32 v47, v32
	v_mov_b32_e32 v52, v32
	v_mov_b32_e32 v53, v32
	v_mov_b32_e32 v54, v32
	v_mov_b32_e32 v55, v32
	v_mov_b32_e32 v60, v32
	v_mov_b32_e32 v61, v32
	v_mov_b32_e32 v62, v32
	v_mov_b32_e32 v63, v32
	v_mov_b32_e32 v68, v32
	v_mov_b32_e32 v69, v32
	v_mov_b32_e32 v70, v32
	v_mov_b32_e32 v71, v32
	v_mov_b32_e32 v76, v32
	v_mov_b32_e32 v77, v32
	v_mov_b32_e32 v78, v32
	v_mov_b32_e32 v79, v32
	v_mov_b32_e32 v84, v32
	v_mov_b32_e32 v85, v32
	v_mov_b32_e32 v86, v32
	v_mov_b32_e32 v87, v32
	v_mov_b32_e32 v88, v32
	v_mov_b32_e32 v89, v32
	v_mov_b32_e32 v90, v32
	v_mov_b32_e32 v91, v32
	v_mov_b32_e32 v92, v32
	v_mov_b32_e32 v93, v32
	v_mov_b32_e32 v94, v32
	v_mov_b32_e32 v95, v32
	v_mov_b32_e32 v96, v32
	v_mov_b32_e32 v97, v32
	v_mov_b32_e32 v98, v32
	v_mov_b32_e32 v99, v32
	v_mov_b32_e32 v100, v32
	v_mov_b32_e32 v101, v32
	v_mov_b32_e32 v102, v32
	v_mov_b32_e32 v103, v32
	v_mov_b32_e32 v104, v32
	v_mov_b32_e32 v105, v32
	v_mov_b32_e32 v106, v32
	v_mov_b32_e32 v107, v32
	v_mov_b32_e32 v112, v32
	v_mov_b32_e32 v113, v32
	v_mov_b32_e32 v114, v32
	v_mov_b32_e32 v115, v32
	v_mov_b32_e32 v120, v32
	v_mov_b32_e32 v121, v32
	v_mov_b32_e32 v122, v32
	v_mov_b32_e32 v123, v32
	v_mov_b32_e32 v128, v32
	v_mov_b32_e32 v129, v32
	v_mov_b32_e32 v130, v32
	v_mov_b32_e32 v131, v32
	v_mov_b32_e32 v136, v32
	v_mov_b32_e32 v137, v32
	v_mov_b32_e32 v138, v32
	v_mov_b32_e32 v139, v32
	v_mov_b32_e32 v144, v32
	v_mov_b32_e32 v145, v32
	v_mov_b32_e32 v146, v32
	v_mov_b32_e32 v147, v32
	v_mov_b32_e32 v108, v32
	v_mov_b32_e32 v109, v32
	v_mov_b32_e32 v110, v32
	v_mov_b32_e32 v111, v32
	v_mov_b32_e32 v116, v32
	v_mov_b32_e32 v117, v32
	v_mov_b32_e32 v118, v32
	v_mov_b32_e32 v119, v32
	v_mov_b32_e32 v124, v32
	v_mov_b32_e32 v125, v32
	v_mov_b32_e32 v126, v32
	v_mov_b32_e32 v127, v32
	v_mov_b32_e32 v132, v32
	v_mov_b32_e32 v133, v32
	v_mov_b32_e32 v134, v32
	v_mov_b32_e32 v135, v32
	v_mov_b32_e32 v140, v32
	v_mov_b32_e32 v141, v32
	v_mov_b32_e32 v142, v32
	v_mov_b32_e32 v143, v32
	v_mov_b32_e32 v148, v32
	v_mov_b32_e32 v149, v32
	v_mov_b32_e32 v150, v32
	v_mov_b32_e32 v151, v32
	v_mov_b32_e32 v152, v32
	v_mov_b32_e32 v153, v32
	v_mov_b32_e32 v154, v32
	v_mov_b32_e32 v155, v32
	v_mov_b32_e32 v156, v32
	v_mov_b32_e32 v157, v32
	v_mov_b32_e32 v158, v32
	v_mov_b32_e32 v159, v32
	.p2align	6
